# attention B: running-max subtraction folded into the QK MFMA (extra k-step against a -1 column in the K-row padding; max reference kept bf16-exact), on top of the max-free fast path
# speedup vs baseline: 1.0172x; 1.0036x over previous
; #define LAS __attribute__((address_space(3)))
; #define GAS __attribute__((address_space(1)))
; DI int opaque_tid() { int t = threadIdx.x; asm volatile("" : "+v"(t)); return t; }
; template <int DQK, int NMAP, int MODE>
; DI void attn_unit(LAS unsigned char* lds, const AttnU& a) {
;     ...
;     const int tid = opaque_tid(), lane = tid & 63, r = lane & 31, h = lane >> 5, wid = __builtin_amdgcn_readfirstlane(tid >> 6);
;     const int nt = 4 + (a.lt1 - a.lt0);
;     const int kr0 = tid / CPR, kc0 = tid % CPR; const int c1 = tid + NTHR; const bool has1 = (64 * CPR > NTHR) && (c1 < 64 * CPR); const int kr1 = c1 / CPR, kc1 = c1 % CPR;
;     const int vr = tid >> 3, vc = tid & 7;
;     u32x4 kq0[3], kq1[3], vq[3];
; #pragma unroll
;     for (int q = 0; q < 3; ++q) { kq0[q] = (u32x4){0, 0, 0, 0}; kq1[q] = (u32x4){0, 0, 0, 0}; vq[q] = (u32x4){0, 0, 0, 0}; }
;     ...
;     ATT_LOAD(0, 0); ATT_LOAD(1, 1); ATT_LOAD(2, 2);
;     if (MODE == 1) { LAS float* rl = (LAS float*)(lds + OFF_RPB); for (int i = tid; i < 465; i += NTHR) rl[i] = ((const GAS float*)a.rpb)[i] * LOG2E; }
;     bf16x8 qf[NMAP][NKS];
;     { const bf16_t* qp = a.Q + (size_t)(32 * wid + r) * a.qs + 8 * h;
; #pragma unroll
;       for (int mp = 0; mp < NMAP; ++mp)
; #pragma unroll
;           for (int s = 0; s < NKS; ++s) qf[mp][s] = *(const GAS bf16x8*)(qp + mp * DQM + 16 * s); }
;     float mref[NMAP], lrun[NMAP]; f32x16 o[NMAP][2];
; #pragma unroll
;     for (int mp = 0; mp < NMAP; ++mp) { mref[mp] = a.m0; lrun[mp] = (h == 0) ? a.l0 : 0.f;
; #pragma unroll
;         for (int e = 0; e < 2; ++e)
; #pragma unroll
;             for (int i = 0; i < 16; ++i) o[mp][e][i] = 0.f; }
;     const int qw0 = a.q0 + 32 * wid;
;     MaskP mk; mk.qrow = qw0 >> 6; mk.qcol = (qw0 & 63) + r; mk.qpos = qw0 + r; mk.rpbl = (const LAS float*)(lds + OFF_RPB); mk.lt = 0;
;     { int rs = mk.qrow - 4; mk.rs = rs < 0 ? 0 : (rs > 120 ? 120 : rs); int cs = mk.qcol - 8; mk.cs = cs < 0 ? 0 : (cs > 48 ? 48 : cs); }
;     ...
;     const LAS unsigned char* vlane = lds + OFF_V + (4 * h + ((lane & 15) >> 2)) * VP + ((lane >> 4) & 1) * 32 + (lane & 3) * 8;
;     f32x16 S[2]; bf16x8 pk[NMAP][2][2];
;     ATT_STORE(0, 0, 0);
;     __syncthreads();
.LBB0_573:
	s_lshl_b64 s[0:1], s[70:71], 9
	v_readlane_b32 s3, v254, 42
	s_add_u32 s0, s3, s0
	v_readlane_b32 s3, v254, 43
	s_addc_u32 s1, s3, s1
	s_lshl_b32 s3, s88, 1
	s_add_u32 s8, s0, s3
	s_addc_u32 s9, s1, 0
	v_readlane_b32 s0, v254, 44
	v_mov_b32_e32 v16, v193
	s_add_u32 s0, s0, s3
	v_readlane_b32 s1, v254, 45
	s_addc_u32 s1, s1, 0
	v_ashrrev_i32_e32 v0, 31, v16
	v_readlane_b32 s4, v254, 56
	v_lshrrev_b32_e32 v0, 29, v0
	s_add_u32 s4, s4, s3
	v_readlane_b32 s3, v254, 57
	v_add_u32_e32 v0, v16, v0
	s_addc_u32 s5, s3, 0
	v_ashrrev_i32_e32 v200, 3, v0
	s_lshl_b32 s3, s77, 8
	v_ashrrev_i32_e32 v202, 3, v16
	v_and_b32_e32 v0, -8, v0
	s_or_b32 s60, s3, 0x10000
	v_ashrrev_i32_e32 v201, 31, v200
	v_sub_u32_e32 v17, v16, v0
	v_lshl_add_u64 v[2:3], v[200:201], 0, s[60:61]
	v_add_u32_e32 v0, s60, v202
	s_or_b32 s60, s3, 0x10040
	v_lshlrev_b32_e32 v4, 3, v17
	v_lshl_add_u64 v[14:15], v[200:201], 0, s[60:61]
	v_ashrrev_i32_e32 v5, 31, v4
	v_lshlrev_b64 v[14:15], 9, v[14:15]
	v_lshlrev_b64 v[10:11], 1, v[4:5]
	v_lshl_add_u64 v[14:15], s[0:1], 0, v[14:15]
	v_lshl_add_u64 v[14:15], v[14:15], 0, v[10:11]
	v_mov_b64_e32 v[12:13], s[4:5]
	global_load_dwordx4 v[148:151], v[14:15], off
	v_add_u32_e32 v14, s60, v202
	s_or_b32 s60, s3, 0x10080
	v_mad_i64_i32 v[6:7], s[10:11], v0, s78, v[12:13]
	v_lshlrev_b32_e32 v0, 4, v16
	v_add_u32_e32 v19, s60, v202
	v_and_b32_e32 v0, 0x70, v0
	v_readfirstlane_b32 s12, v16
	v_mad_i64_i32 v[14:15], s[10:11], v14, s78, v[12:13]
	v_mad_i64_i32 v[12:13], s[10:11], v19, s78, v[12:13]
	v_lshl_add_u64 v[6:7], v[6:7], 0, v[0:1]
	v_lshl_add_u64 v[12:13], v[12:13], 0, v[0:1]
	s_ashr_i32 s10, s12, 1
	global_load_dwordx4 v[6:9], v[6:7], off
	v_lshl_add_u64 v[14:15], v[14:15], 0, v[0:1]
	global_load_dwordx4 v[172:175], v[12:13], off
	v_mov_b32_e32 v12, s10
	v_bfi_b32 v196, s20, v12, v16
	v_ashrrev_i32_e32 v197, 31, v196
	v_lshlrev_b64 v[2:3], 9, v[2:3]
	v_bfe_u32 v18, v16, 5, 1
	global_load_dwordx4 v[152:155], v[14:15], off
	v_lshl_add_u64 v[14:15], v[200:201], 0, s[60:61]
	v_lshlrev_b64 v[12:13], 9, v[196:197]
	v_lshl_add_u64 v[2:3], s[0:1], 0, v[2:3]
	v_lshlrev_b64 v[14:15], 9, v[14:15]
	v_lshl_add_u64 v[12:13], s[8:9], 0, v[12:13]
	v_lshlrev_b32_e32 v204, 4, v18
	v_mov_b32_e32 v205, v1
	v_lshl_add_u64 v[2:3], v[2:3], 0, v[10:11]
	v_lshl_add_u64 v[14:15], s[0:1], 0, v[14:15]
	v_lshl_add_u64 v[12:13], v[12:13], 0, v[204:205]
	global_load_dwordx4 v[2:5], v[2:3], off
	v_lshl_add_u64 v[14:15], v[14:15], 0, v[10:11]
	global_load_dwordx4 v[156:159], v[12:13], off
	global_load_dwordx4 v[160:163], v[12:13], off offset:32
	global_load_dwordx4 v[164:167], v[12:13], off offset:64
	global_load_dwordx4 v[168:171], v[12:13], off offset:96
	global_load_dwordx4 v[176:179], v[14:15], off
	s_or_b32 s10, s76, 6
	v_lshrrev_b32_e32 v13, 2, v16
	v_lshlrev_b32_e32 v15, 3, v16
	v_lshlrev_b32_e32 v205, 2, v18
	s_mul_i32 s11, s10, 0xab
	v_lshlrev_b32_e32 v14, 1, v16
	v_and_b32_e32 v237, 24, v15
	v_mul_lo_u32 v15, v202, s21
	v_and_or_b32 v13, v13, 3, v205
	s_lshr_b32 s11, s11, 9
	v_and_b32_e32 v14, 32, v14
	v_add_u32_e32 v15, 0, v15
	v_mul_u32_u24_e32 v13, 0x90, v13
	v_mul_lo_u32 v239, v200, s21
	v_lshlrev_b32_e32 v240, 4, v17
	s_mul_i32 s11, s11, 3
	v_and_b32_e32 v12, 31, v16
	v_add3_u32 v238, 0, v13, v14
	v_add3_u32 v241, 0, v239, v240
	v_add_u32_e32 v242, v15, v0
	s_sub_i32 s11, s10, s11
	v_mov_b32_e32 v14, v1
	v_mov_b32_e32 v15, v1
	v_lshlrev_b32_e32 v198, 3, v18
	s_and_b32 s11, s11, 0xff
	v_mul_u32_u24_e32 v243, 0x90, v12
	v_lshl_add_u64 v[206:207], s[0:1], 0, v[10:11]
	v_lshl_add_u64 v[208:209], s[4:5], 0, v[0:1]
	s_lshl_b32 s0, s77, 13
	v_mov_b32_e32 v0, v1
	v_mov_b32_e32 v10, v1
	v_mov_b32_e32 v11, v1
	v_mov_b32_e32 v12, v1
	v_mov_b32_e32 v13, v1
	v_ashrrev_i32_e32 v203, 31, v202
	s_or_b32 s8, s76, 3
	s_or_b32 s9, s76, 4
	s_sub_i32 s10, s10, s11
	s_or_b32 s11, s76, 2
	s_addk_i32 s0, 0xff00
	s_or_b32 s1, s3, 0x100c0
	v_add3_u32 v244, 0, v243, v204
	s_mov_b32 s12, 0
	v_mov_b32_e32 v236, 0
	v_mov_b32_e32 v210, 0xf149f2ca
	v_mov_b32_e32 v212, 0xf149f2ca
	v_mov_b32_e32 v245, 0
	s_waitcnt vmcnt(0)
	ds_write_b128 v241, v[2:5]
	ds_write_b128 v242, v[6:9] offset:18432
	v_mov_b32_e32 v2, v1
	v_mov_b32_e32 v3, v1
	v_mov_b32_e32 v4, v1
	v_mov_b32_e32 v5, v1
	v_mov_b32_e32 v6, v1
	v_mov_b32_e32 v7, v1
	v_mov_b32_e32 v8, v1
	v_mov_b32_e32 v9, v1
	v_mov_b64_e32 v[30:31], v[14:15]
	v_mov_b64_e32 v[62:63], v[14:15]
	v_mov_b64_e32 v[46:47], v[14:15]
	v_mov_b64_e32 v[78:79], v[14:15]
	v_mov_b64_e32 v[28:29], v[12:13]
	v_mov_b64_e32 v[26:27], v[10:11]
	v_mov_b64_e32 v[24:25], v[8:9]
	v_mov_b64_e32 v[22:23], v[6:7]
	v_mov_b64_e32 v[20:21], v[4:5]
	v_mov_b64_e32 v[18:19], v[2:3]
	v_mov_b64_e32 v[16:17], v[0:1]
	v_mov_b64_e32 v[60:61], v[12:13]
	v_mov_b64_e32 v[58:59], v[10:11]
	v_mov_b64_e32 v[56:57], v[8:9]
	v_mov_b64_e32 v[54:55], v[6:7]
	v_mov_b64_e32 v[52:53], v[4:5]
	v_mov_b64_e32 v[50:51], v[2:3]
	v_mov_b64_e32 v[48:49], v[0:1]
	v_mov_b64_e32 v[44:45], v[12:13]
	v_mov_b64_e32 v[42:43], v[10:11]
	v_mov_b64_e32 v[40:41], v[8:9]
	v_mov_b64_e32 v[38:39], v[6:7]
	v_mov_b64_e32 v[36:37], v[4:5]
	v_mov_b64_e32 v[34:35], v[2:3]
	v_mov_b64_e32 v[32:33], v[0:1]
	v_mov_b64_e32 v[76:77], v[12:13]
	v_mov_b64_e32 v[74:75], v[10:11]
	v_mov_b64_e32 v[72:73], v[8:9]
	v_mov_b64_e32 v[70:71], v[6:7]
	v_mov_b64_e32 v[68:69], v[4:5]
	v_mov_b64_e32 v[66:67], v[2:3]
	v_mov_b64_e32 v[64:65], v[0:1]
	v_and_b32_e32 v0, 63, v193
	v_mul_u32_u24_e32 v0, 0x90, v0
	v_bfe_u32 v14, v193, 6, 1
	v_mul_u32_u24_e32 v14, 0x2400, v14
	v_add_u32_e32 v0, v0, v14
	v_mov_b32_e32 v230, 0xbf80
	v_mov_b32_e32 v231, 0
	v_mov_b32_e32 v232, 0
	v_mov_b32_e32 v233, 0
	ds_write_b128 v0, v[230:233] offset:128
	s_waitcnt lgkmcnt(0)
	s_barrier
	s_waitcnt vmcnt(0)
; #define LAS __attribute__((address_space(3)))
; template <int DQK, int NMAP>
; DI void att_qk(const LAS unsigned char* Kb, int r, int h, const bf16x8 (&qfm)[DQK / NMAP / 16], int mp, f32x16 (&S)[2]) {
;     constexpr int DQM = DQK / NMAP, NKS = DQM / 16, KP = DQK * 2 + 16, CH = (NKS > 4) ? 3 : NKS;
;     const LAS unsigned char* kp = Kb + r * KP + (mp * DQM + 8 * h) * 2;
;     const f32x16 z = {0.f, 0.f, 0.f, 0.f, 0.f, 0.f, 0.f, 0.f, 0.f, 0.f, 0.f, 0.f, 0.f, 0.f, 0.f, 0.f};
; #pragma unroll
;     for (int c = 0; c < NKS / CH; ++c) {
;         bf16x8 kf[2 * CH];
; #pragma unroll
;         for (int s = 0; s < CH; ++s) { kf[2 * s] = *(const LAS bf16x8*)(kp + 32 * (c * CH + s)); kf[2 * s + 1] = *(const LAS bf16x8*)(kp + 32 * KP + 32 * (c * CH + s)); }
;         __builtin_amdgcn_sched_barrier(0);
;         __builtin_amdgcn_s_setprio(1);
; #pragma unroll
;         for (int s = 0; s < CH; ++s) {
;             if (c == 0 && s == 0) { S[0] = __builtin_amdgcn_mfma_f32_32x32x16_bf16(kf[0], qfm[0], z, 0, 0, 0); S[1] = __builtin_amdgcn_mfma_f32_32x32x16_bf16(kf[1], qfm[0], z, 0, 0, 0); }
;             else { S[0] = __builtin_amdgcn_mfma_f32_32x32x16_bf16(kf[2 * s], qfm[c * CH + s], S[0], 0, 0, 0); S[1] = __builtin_amdgcn_mfma_f32_32x32x16_bf16(kf[2 * s + 1], qfm[c * CH + s], S[1], 0, 0, 0); }
;         }
;         __builtin_amdgcn_s_setprio(0);
;         __builtin_amdgcn_sched_barrier(0);
;     }
; }
.LBB0_574:
	s_add_i32 s13, s12, 3
	s_cmp_lt_u32 s13, s9
	s_cselect_b32 s3, s13, s8
	s_lshl_b32 s4, s3, 6
	s_add_i32 s4, s4, s0
	s_cmp_lt_u32 s3, 4
	s_cselect_b32 s4, s1, s4
	s_ashr_i32 s5, s4, 31
	v_lshl_add_u64 v[2:3], s[4:5], 0, v[200:201]
	v_lshl_add_u64 v[6:7], s[4:5], 0, v[202:203]
	v_lshlrev_b64 v[2:3], 9, v[2:3]
	v_mad_u64_u32 v[8:9], s[4:5], v6, s78, v[208:209]
	v_lshl_add_u64 v[2:3], v[206:207], 0, v[2:3]
	v_mad_i32_i24 v9, v7, s78, v9
	global_load_dwordx4 v[2:5], v[2:3], off
	s_cmp_ge_u32 s12, s9
	global_load_dwordx4 v[6:9], v[8:9], off
	s_cbranch_scc1 .LBB0_580
	s_bitcmp1_b32 s12, 0
	s_cselect_b32 s3, 0x2400, 0
	v_add_u32_e32 v0, s3, v244
	ds_read_b128 v[10:13], v0
	ds_read_b128 v[80:83], v0 offset:32
	ds_read_b128 v[84:87], v0 offset:4608
	ds_read_b128 v[88:91], v0 offset:4640
	ds_read_b128 v[188:191], v0 offset:128
	ds_read_b128 v[246:249], v0 offset:4736
	v_mov_b32_e32 v230, 0
	s_mov_b64 exec, 0xffffffff
	v_cvt_pk_bf16_f32 v230, v212, 0
	s_mov_b64 exec, -1
	s_setprio 1
	s_waitcnt lgkmcnt(5)
	v_mfma_f32_32x32x16_bf16 v[112:127], v[10:13], v[156:159], 0
	s_waitcnt lgkmcnt(3)
	v_mfma_f32_32x32x16_bf16 v[128:143], v[84:87], v[156:159], 0
	v_mfma_f32_32x32x16_bf16 v[112:127], v[80:83], v[160:163], v[112:127]
	s_waitcnt lgkmcnt(2)
	v_mfma_f32_32x32x16_bf16 v[128:143], v[88:91], v[160:163], v[128:143]
	s_waitcnt lgkmcnt(1)
	v_mfma_f32_32x32x16_bf16 v[112:127], v[188:191], v[230:233], v[112:127]
	s_waitcnt lgkmcnt(0)
	v_mfma_f32_32x32x16_bf16 v[128:143], v[246:249], v[230:233], v[128:143]
	s_setprio 0
	v_mov_b32_e32 v230, 0
	s_mov_b64 exec, 0xffffffff
	v_cvt_pk_bf16_f32 v230, v210, 0
	s_mov_b64 exec, -1
	ds_read_b128 v[10:13], v0 offset:64
	ds_read_b128 v[180:183], v0 offset:96
	ds_read_b128 v[96:99], v0 offset:4672
	ds_read_b128 v[184:187], v0 offset:4704
	s_setprio 1
	s_waitcnt lgkmcnt(3)
	v_mfma_f32_32x32x16_bf16 v[80:95], v[10:13], v[164:167], 0
	s_waitcnt lgkmcnt(1)
	v_mfma_f32_32x32x16_bf16 v[96:111], v[96:99], v[164:167], 0
	v_mfma_f32_32x32x16_bf16 v[80:95], v[180:183], v[168:171], v[80:95]
	s_waitcnt lgkmcnt(0)
	v_mfma_f32_32x32x16_bf16 v[96:111], v[184:187], v[168:171], v[96:111]
	v_mfma_f32_32x32x16_bf16 v[80:95], v[188:191], v[230:233], v[80:95]
	v_mfma_f32_32x32x16_bf16 v[96:111], v[246:249], v[230:233], v[96:111]
	s_setprio 0
	v_add_u32_e32 v0, v238, v237
	ds_read_b64_tr_b16 v[188:189], v0 offset:18432
	ds_read_b64_tr_b16 v[190:191], v0 offset:19584
	ds_read_b64_tr_b16 v[184:185], v0 offset:20736
	ds_read_b64_tr_b16 v[186:187], v0 offset:21888
	ds_read_b64_tr_b16 v[180:181], v0 offset:23040
	ds_read_b64_tr_b16 v[182:183], v0 offset:24192
	ds_read_b64_tr_b16 v[10:11], v0 offset:25344
	ds_read_b64_tr_b16 v[12:13], v0 offset:26496
	s_nop 1
	v_exp_f32_e32 v14, v112
	v_exp_f32_e32 v15, v113
	v_exp_f32_e32 v112, v128
	v_exp_f32_e32 v113, v129
	v_exp_f32_e32 v114, v114
	v_exp_f32_e32 v115, v115
	v_exp_f32_e32 v128, v130
	v_exp_f32_e32 v129, v131
	v_pk_add_f32 v[130:131], v[14:15], 0 op_sel_hi:[1,0]
	v_exp_f32_e32 v116, v116
	v_exp_f32_e32 v117, v117
	v_pk_add_f32 v[130:131], v[112:113], v[130:131]
	v_exp_f32_e32 v132, v132
	v_exp_f32_e32 v133, v133
	v_pk_add_f32 v[130:131], v[114:115], v[130:131]
	v_exp_f32_e32 v118, v118
	v_exp_f32_e32 v119, v119
	v_pk_add_f32 v[130:131], v[128:129], v[130:131]
	v_exp_f32_e32 v134, v134
	v_exp_f32_e32 v135, v135
	v_pk_add_f32 v[130:131], v[116:117], v[130:131]
	v_exp_f32_e32 v246, v120
	v_exp_f32_e32 v247, v121
	v_pk_add_f32 v[130:131], v[132:133], v[130:131]
	v_exp_f32_e32 v136, v136
	v_exp_f32_e32 v137, v137
	v_pk_add_f32 v[130:131], v[118:119], v[130:131]
	v_exp_f32_e32 v248, v138
	v_exp_f32_e32 v138, v122
	v_exp_f32_e32 v249, v139
	v_exp_f32_e32 v139, v123
	v_pk_add_f32 v[130:131], v[134:135], v[130:131]
	v_pk_add_f32 v[120:121], v[246:247], v[130:131]
	v_exp_f32_e32 v130, v124
	v_exp_f32_e32 v131, v125
	v_pk_add_f32 v[120:121], v[136:137], v[120:121]
	v_exp_f32_e32 v140, v140
	v_exp_f32_e32 v141, v141
	v_pk_add_f32 v[120:121], v[138:139], v[120:121]
	v_exp_f32_e32 v250, v142
	v_exp_f32_e32 v142, v126
	v_exp_f32_e32 v251, v143
	v_exp_f32_e32 v143, v127
	v_pk_add_f32 v[120:121], v[248:249], v[120:121]
	v_pk_add_f32 v[120:121], v[130:131], v[120:121]
	v_cvt_pk_bf16_f32 v122, v116, v117
	v_pk_add_f32 v[120:121], v[140:141], v[120:121]
	v_cvt_pk_bf16_f32 v123, v118, v119
	v_pk_add_f32 v[120:121], v[142:143], v[120:121]
	v_cvt_pk_bf16_f32 v112, v112, v113
	v_pk_add_f32 v[120:121], v[250:251], v[120:121]
	v_cvt_pk_bf16_f32 v113, v128, v129
	v_add_f32_e32 v120, v120, v121
	v_mov_b32_e32 v230, v120
	v_cvt_pk_bf16_f32 v120, v14, v15
	v_cvt_pk_bf16_f32 v121, v114, v115
	v_cvt_pk_bf16_f32 v114, v132, v133
	v_cvt_pk_bf16_f32 v115, v134, v135
	v_cvt_pk_bf16_f32 v124, v246, v247
	v_cvt_pk_bf16_f32 v125, v138, v139
	v_cvt_pk_bf16_f32 v126, v130, v131
	v_cvt_pk_bf16_f32 v127, v142, v143
	v_cvt_pk_bf16_f32 v116, v136, v137
	v_cvt_pk_bf16_f32 v117, v248, v249
	v_cvt_pk_bf16_f32 v118, v140, v141
	v_cvt_pk_bf16_f32 v119, v250, v251
	v_exp_f32_e32 v14, v80
	v_exp_f32_e32 v15, v81
	v_exp_f32_e32 v96, v96
	v_exp_f32_e32 v97, v97
	v_exp_f32_e32 v82, v82
	v_exp_f32_e32 v83, v83
	v_exp_f32_e32 v98, v98
	v_exp_f32_e32 v99, v99
	v_pk_add_f32 v[80:81], v[14:15], 0 op_sel_hi:[1,0]
	v_exp_f32_e32 v84, v84
	v_exp_f32_e32 v85, v85
	v_pk_add_f32 v[80:81], v[96:97], v[80:81]
	v_exp_f32_e32 v100, v100
	v_exp_f32_e32 v101, v101
	v_pk_add_f32 v[80:81], v[82:83], v[80:81]
	v_exp_f32_e32 v86, v86
	v_exp_f32_e32 v87, v87
	v_pk_add_f32 v[80:81], v[98:99], v[80:81]
	v_exp_f32_e32 v102, v102
	v_exp_f32_e32 v103, v103
	v_pk_add_f32 v[80:81], v[84:85], v[80:81]
	v_exp_f32_e32 v88, v88
	v_exp_f32_e32 v89, v89
	v_pk_add_f32 v[80:81], v[100:101], v[80:81]
	v_exp_f32_e32 v104, v104
	v_exp_f32_e32 v105, v105
	v_pk_add_f32 v[80:81], v[86:87], v[80:81]
	s_nop 0
	v_pk_add_f32 v[80:81], v[102:103], v[80:81]
	s_nop 0
	v_pk_add_f32 v[80:81], v[88:89], v[80:81]
	s_nop 0
	v_pk_add_f32 v[80:81], v[104:105], v[80:81]
	v_exp_f32_e32 v90, v90
	v_exp_f32_e32 v91, v91
	v_exp_f32_e32 v106, v106
	v_exp_f32_e32 v107, v107
	v_exp_f32_e32 v92, v92
	v_exp_f32_e32 v93, v93
	v_exp_f32_e32 v108, v108
	v_exp_f32_e32 v109, v109
	v_pk_add_f32 v[80:81], v[90:91], v[80:81]
	v_exp_f32_e32 v94, v94
	v_exp_f32_e32 v95, v95
	v_pk_add_f32 v[80:81], v[106:107], v[80:81]
	v_exp_f32_e32 v110, v110
	v_exp_f32_e32 v111, v111
	v_pk_add_f32 v[80:81], v[92:93], v[80:81]
	s_nop 0
	v_pk_add_f32 v[80:81], v[108:109], v[80:81]
	s_nop 0
	v_pk_add_f32 v[80:81], v[94:95], v[80:81]
	s_nop 0
	v_pk_add_f32 v[80:81], v[110:111], v[80:81]
	s_nop 0
	v_add_f32_e32 v80, v80, v81
	v_cmp_nge_f32_e32 vcc, 0x43800000, v230
	s_mov_b64 s[4:5], vcc
	v_cmp_nge_f32_e32 vcc, 0x43800000, v80
	s_or_b64 vcc, vcc, s[4:5]
	s_cbranch_vccnz .LB_slow0
; #define LAS __attribute__((address_space(3)))
; template <int DQK, int NMAP>
; DI void att_qk(const LAS unsigned char* Kb, int r, int h, const bf16x8 (&qfm)[DQK / NMAP / 16], int mp, f32x16 (&S)[2]) {
;     constexpr int DQM = DQK / NMAP, NKS = DQM / 16, KP = DQK * 2 + 16, CH = (NKS > 4) ? 3 : NKS;
;     const LAS unsigned char* kp = Kb + r * KP + (mp * DQM + 8 * h) * 2;
;     const f32x16 z = {0.f, 0.f, 0.f, 0.f, 0.f, 0.f, 0.f, 0.f, 0.f, 0.f, 0.f, 0.f, 0.f, 0.f, 0.f, 0.f};
; #pragma unroll
;     for (int c = 0; c < NKS / CH; ++c) {
;         bf16x8 kf[2 * CH];
; #pragma unroll
;         for (int s = 0; s < CH; ++s) { kf[2 * s] = *(const LAS bf16x8*)(kp + 32 * (c * CH + s)); kf[2 * s + 1] = *(const LAS bf16x8*)(kp + 32 * KP + 32 * (c * CH + s)); }
;         __builtin_amdgcn_sched_barrier(0);
;         __builtin_amdgcn_s_setprio(1);
; #pragma unroll
;         for (int s = 0; s < CH; ++s) {
;             if (c == 0 && s == 0) { S[0] = __builtin_amdgcn_mfma_f32_32x32x16_bf16(kf[0], qfm[0], z, 0, 0, 0); S[1] = __builtin_amdgcn_mfma_f32_32x32x16_bf16(kf[1], qfm[0], z, 0, 0, 0); }
;             else { S[0] = __builtin_amdgcn_mfma_f32_32x32x16_bf16(kf[2 * s], qfm[c * CH + s], S[0], 0, 0, 0); S[1] = __builtin_amdgcn_mfma_f32_32x32x16_bf16(kf[2 * s + 1], qfm[c * CH + s], S[1], 0, 0, 0); }
;         }
;         __builtin_amdgcn_s_setprio(0);
;         __builtin_amdgcn_sched_barrier(0);
;     }
; }
	v_add_f32_e32 v245, v245, v230
	v_add_f32_e32 v236, v236, v80
	s_waitcnt lgkmcnt(6)
	v_mfma_f32_32x32x16_bf16 v[64:79], v[188:191], v[120:123], v[64:79]
	s_waitcnt lgkmcnt(4)
	v_mfma_f32_32x32x16_bf16 v[64:79], v[184:187], v[124:127], v[64:79]
	v_cvt_pk_bf16_f32 v80, v14, v15
	v_cvt_pk_bf16_f32 v81, v82, v83
	v_cvt_pk_bf16_f32 v82, v84, v85
	v_cvt_pk_bf16_f32 v83, v86, v87
	v_cvt_pk_bf16_f32 v84, v96, v97
	v_cvt_pk_bf16_f32 v85, v98, v99
	s_waitcnt lgkmcnt(2)
	v_mfma_f32_32x32x16_bf16 v[64:79], v[180:183], v[112:115], v[64:79]
	v_cvt_pk_bf16_f32 v86, v100, v101
	v_cvt_pk_bf16_f32 v87, v102, v103
	v_cvt_pk_bf16_f32 v88, v88, v89
	v_cvt_pk_bf16_f32 v89, v90, v91
	v_cvt_pk_bf16_f32 v90, v92, v93
	v_cvt_pk_bf16_f32 v91, v94, v95
	v_cvt_pk_bf16_f32 v92, v104, v105
	v_cvt_pk_bf16_f32 v93, v106, v107
	v_cvt_pk_bf16_f32 v94, v108, v109
	v_cvt_pk_bf16_f32 v95, v110, v111
	s_waitcnt lgkmcnt(0)
	v_mfma_f32_32x32x16_bf16 v[64:79], v[10:13], v[116:119], v[64:79]
	v_mfma_f32_32x32x16_bf16 v[48:63], v[188:191], v[80:83], v[48:63]
	v_mfma_f32_32x32x16_bf16 v[48:63], v[184:187], v[88:91], v[48:63]
	v_mfma_f32_32x32x16_bf16 v[48:63], v[180:183], v[84:87], v[48:63]
	v_mfma_f32_32x32x16_bf16 v[48:63], v[10:13], v[92:95], v[48:63]
	ds_read_b64_tr_b16 v[10:11], v0 offset:18496
	ds_read_b64_tr_b16 v[12:13], v0 offset:19648
	ds_read_b64_tr_b16 v[96:97], v0 offset:20800
	ds_read_b64_tr_b16 v[98:99], v0 offset:21952
	ds_read_b64_tr_b16 v[100:101], v0 offset:23104
	ds_read_b64_tr_b16 v[102:103], v0 offset:24256
	ds_read_b64_tr_b16 v[104:105], v0 offset:25408
	ds_read_b64_tr_b16 v[106:107], v0 offset:26560
	s_setprio 1
	s_waitcnt lgkmcnt(6)
	v_mfma_f32_32x32x16_bf16 v[32:47], v[10:13], v[120:123], v[32:47]
	v_mfma_f32_32x32x16_bf16 v[16:31], v[10:13], v[80:83], v[16:31]
	s_waitcnt lgkmcnt(4)
	v_mfma_f32_32x32x16_bf16 v[32:47], v[96:99], v[124:127], v[32:47]
	v_mfma_f32_32x32x16_bf16 v[16:31], v[96:99], v[88:91], v[16:31]
	s_waitcnt lgkmcnt(2)
	v_mfma_f32_32x32x16_bf16 v[32:47], v[100:103], v[112:115], v[32:47]
	v_mfma_f32_32x32x16_bf16 v[16:31], v[100:103], v[84:87], v[16:31]
	s_waitcnt lgkmcnt(0)
	v_mfma_f32_32x32x16_bf16 v[32:47], v[104:107], v[116:119], v[32:47]
	v_mfma_f32_32x32x16_bf16 v[16:31], v[104:107], v[92:95], v[16:31]
	s_setprio 0
.LBB0_580:
	s_add_i32 s14, s12, 1
	s_bitcmp1_b32 s14, 0
	s_cselect_b32 s3, 0x2400, 0
	s_add_i32 s3, s3, 0
	s_add_i32 s4, s12, 4
	s_cmp_lt_u32 s12, s76
	s_cselect_b32 s4, s4, s8
	s_lshl_b32 s5, s4, 6
	s_add_i32 s5, s5, s0
	s_cmp_lt_u32 s4, 4
	s_cselect_b32 s4, s1, s5
	s_ashr_i32 s5, s4, 31
	v_lshl_add_u64 v[10:11], s[4:5], 0, v[200:201]
	v_lshlrev_b64 v[10:11], 9, v[10:11]
	v_add3_u32 v0, s3, v239, v240
	v_lshl_add_u64 v[10:11], v[206:207], 0, v[10:11]
	s_waitcnt vmcnt(5)
	ds_write_b128 v0, v[148:151]
	s_waitcnt vmcnt(4)
	ds_write_b128 v242, v[152:155] offset:27648
	s_waitcnt lgkmcnt(0)
	s_barrier
	global_load_dwordx4 v[148:151], v[10:11], off
	v_lshl_add_u64 v[10:11], s[4:5], 0, v[202:203]
	v_mad_u64_u32 v[12:13], s[4:5], v10, s78, v[208:209]
	v_mad_i32_i24 v13, v11, s78, v13
	global_load_dwordx4 v[152:155], v[12:13], off
	s_cmp_ge_u32 s14, s9
	s_cbranch_scc1 .LBB0_586
	v_add_u32_e32 v0, s3, v243
	v_add_u32_e32 v0, v0, v204
	ds_read_b128 v[10:13], v0
	ds_read_b128 v[80:83], v0 offset:32
	ds_read_b128 v[84:87], v0 offset:4608
	ds_read_b128 v[88:91], v0 offset:4640
	ds_read_b128 v[188:191], v0 offset:128
	ds_read_b128 v[246:249], v0 offset:4736
	v_mov_b32_e32 v230, 0
	s_mov_b64 exec, 0xffffffff
	v_cvt_pk_bf16_f32 v230, v212, 0
	s_mov_b64 exec, -1
	s_setprio 1
	s_waitcnt lgkmcnt(5)
	v_mfma_f32_32x32x16_bf16 v[112:127], v[10:13], v[156:159], 0
	s_waitcnt lgkmcnt(3)
	v_mfma_f32_32x32x16_bf16 v[128:143], v[84:87], v[156:159], 0
	v_mfma_f32_32x32x16_bf16 v[112:127], v[80:83], v[160:163], v[112:127]
	s_waitcnt lgkmcnt(2)
	v_mfma_f32_32x32x16_bf16 v[128:143], v[88:91], v[160:163], v[128:143]
	s_waitcnt lgkmcnt(1)
	v_mfma_f32_32x32x16_bf16 v[112:127], v[188:191], v[230:233], v[112:127]
	s_waitcnt lgkmcnt(0)
	v_mfma_f32_32x32x16_bf16 v[128:143], v[246:249], v[230:233], v[128:143]
	s_setprio 0
	v_mov_b32_e32 v230, 0
	s_mov_b64 exec, 0xffffffff
	v_cvt_pk_bf16_f32 v230, v210, 0
	s_mov_b64 exec, -1
	ds_read_b128 v[10:13], v0 offset:64
	ds_read_b128 v[180:183], v0 offset:96
	ds_read_b128 v[96:99], v0 offset:4672
	ds_read_b128 v[184:187], v0 offset:4704
	s_setprio 1
	s_waitcnt lgkmcnt(3)
	v_mfma_f32_32x32x16_bf16 v[80:95], v[10:13], v[164:167], 0
	s_waitcnt lgkmcnt(1)
	v_mfma_f32_32x32x16_bf16 v[96:111], v[96:99], v[164:167], 0
	v_mfma_f32_32x32x16_bf16 v[80:95], v[180:183], v[168:171], v[80:95]
	s_waitcnt lgkmcnt(0)
; DI unsigned pk2(float lo, float hi) { f32x2 v = {lo, hi}; bf16x2_t b = __builtin_convertvector(v, bf16x2_t); return __builtin_bit_cast(unsigned, b); }
; DI float fast_exp2(float x) { return __builtin_amdgcn_exp2f(x); }
; DI void att_sm_tail(f32x16 (&S)[2], bf16x8 (&pkm)[2][2], const float mrefm, float& lrunm) {
;     {
;         f32x16& s0 = S[0]; f32x16& s1 = S[1];
;         const f32x2 nm2 = {-mrefm, -mrefm};
;         f32x2 acc2 = {0.f, 0.f};
; #pragma unroll
;         for (int i = 0; i < 16; i += 2) {
;             f32x2 a = {s0[i], s0[i + 1]}, b = {s1[i], s1[i + 1]}; a += nm2; b += nm2;
;             a.x = fast_exp2(a.x); a.y = fast_exp2(a.y); b.x = fast_exp2(b.x); b.y = fast_exp2(b.y);
;             acc2 += a; acc2 += b; s0[i] = a.x; s0[i + 1] = a.y; s1[i] = b.x; s1[i + 1] = b.y;
;         }
;         lrunm += acc2.x + acc2.y;
; #pragma unroll
;         for (int s = 0; s < 2; ++s) {
;             u32x4 w0, w1;
;             w0.x = pk2(s0[8 * s + 0], s0[8 * s + 1]); w0.y = pk2(s0[8 * s + 2], s0[8 * s + 3]); w0.z = pk2(s0[8 * s + 4], s0[8 * s + 5]); w0.w = pk2(s0[8 * s + 6], s0[8 * s + 7]);
;             w1.x = pk2(s1[8 * s + 0], s1[8 * s + 1]); w1.y = pk2(s1[8 * s + 2], s1[8 * s + 3]); w1.z = pk2(s1[8 * s + 4], s1[8 * s + 5]); w1.w = pk2(s1[8 * s + 6], s1[8 * s + 7]);
;             pkm[0][s] = __builtin_bit_cast(bf16x8, w0); pkm[1][s] = __builtin_bit_cast(bf16x8, w1);
;         }
;     }
; }
	v_mfma_f32_32x32x16_bf16 v[96:111], v[184:187], v[168:171], v[96:111]
	v_mfma_f32_32x32x16_bf16 v[80:95], v[188:191], v[230:233], v[80:95]
	v_mfma_f32_32x32x16_bf16 v[96:111], v[246:249], v[230:233], v[96:111]
	s_setprio 0
	v_add_u32_e32 v0, v238, v237
	ds_read_b64_tr_b16 v[190:191], v0 offset:28800
	ds_read_b64_tr_b16 v[180:181], v0 offset:29952
	ds_read_b64_tr_b16 v[182:183], v0 offset:31104
	ds_read_b64_tr_b16 v[10:11], v0 offset:32256
	ds_read_b64_tr_b16 v[188:189], v0 offset:27648
	ds_read_b64_tr_b16 v[12:13], v0 offset:33408
	ds_read_b64_tr_b16 v[184:185], v0 offset:34560
	ds_read_b64_tr_b16 v[186:187], v0 offset:35712
	s_nop 1
	v_exp_f32_e32 v14, v112
	v_exp_f32_e32 v15, v113
	v_exp_f32_e32 v112, v128
	v_exp_f32_e32 v113, v129
	v_exp_f32_e32 v114, v114
	v_exp_f32_e32 v115, v115
	v_exp_f32_e32 v128, v130
	v_exp_f32_e32 v129, v131
	v_pk_add_f32 v[130:131], v[14:15], 0 op_sel_hi:[1,0]
	v_exp_f32_e32 v116, v116
	v_exp_f32_e32 v117, v117
	v_pk_add_f32 v[130:131], v[112:113], v[130:131]
	v_exp_f32_e32 v132, v132
	v_exp_f32_e32 v133, v133
	v_pk_add_f32 v[130:131], v[114:115], v[130:131]
	v_exp_f32_e32 v118, v118
	v_exp_f32_e32 v119, v119
	v_pk_add_f32 v[130:131], v[128:129], v[130:131]
	v_exp_f32_e32 v134, v134
	v_exp_f32_e32 v135, v135
	v_pk_add_f32 v[130:131], v[116:117], v[130:131]
	v_exp_f32_e32 v246, v120
	v_exp_f32_e32 v247, v121
	v_pk_add_f32 v[130:131], v[132:133], v[130:131]
	v_exp_f32_e32 v136, v136
	v_exp_f32_e32 v137, v137
	v_pk_add_f32 v[130:131], v[118:119], v[130:131]
	v_exp_f32_e32 v248, v138
	v_exp_f32_e32 v138, v122
	v_exp_f32_e32 v249, v139
	v_exp_f32_e32 v139, v123
	v_pk_add_f32 v[130:131], v[134:135], v[130:131]
	v_pk_add_f32 v[120:121], v[246:247], v[130:131]
	v_exp_f32_e32 v130, v124
	v_exp_f32_e32 v131, v125
	v_pk_add_f32 v[120:121], v[136:137], v[120:121]
	v_exp_f32_e32 v140, v140
	v_exp_f32_e32 v141, v141
	v_pk_add_f32 v[120:121], v[138:139], v[120:121]
	v_exp_f32_e32 v250, v142
	v_exp_f32_e32 v142, v126
	v_exp_f32_e32 v251, v143
	v_exp_f32_e32 v143, v127
	v_pk_add_f32 v[120:121], v[248:249], v[120:121]
	v_pk_add_f32 v[120:121], v[130:131], v[120:121]
	v_cvt_pk_bf16_f32 v122, v116, v117
	v_pk_add_f32 v[120:121], v[140:141], v[120:121]
	v_cvt_pk_bf16_f32 v123, v118, v119
	v_pk_add_f32 v[120:121], v[142:143], v[120:121]
	v_cvt_pk_bf16_f32 v112, v112, v113
	v_pk_add_f32 v[120:121], v[250:251], v[120:121]
	v_cvt_pk_bf16_f32 v113, v128, v129
	v_add_f32_e32 v120, v120, v121
	v_mov_b32_e32 v230, v120
	v_cvt_pk_bf16_f32 v120, v14, v15
	v_cvt_pk_bf16_f32 v121, v114, v115
	v_cvt_pk_bf16_f32 v114, v132, v133
	v_cvt_pk_bf16_f32 v115, v134, v135
	v_cvt_pk_bf16_f32 v124, v246, v247
	v_cvt_pk_bf16_f32 v125, v138, v139
	v_cvt_pk_bf16_f32 v126, v130, v131
	v_cvt_pk_bf16_f32 v127, v142, v143
	v_cvt_pk_bf16_f32 v116, v136, v137
	v_cvt_pk_bf16_f32 v117, v248, v249
	v_cvt_pk_bf16_f32 v118, v140, v141
	v_cvt_pk_bf16_f32 v119, v250, v251
	v_exp_f32_e32 v14, v80
	v_exp_f32_e32 v15, v81
	v_exp_f32_e32 v96, v96
	v_exp_f32_e32 v97, v97
	v_exp_f32_e32 v82, v82
	v_exp_f32_e32 v83, v83
	v_exp_f32_e32 v98, v98
	v_exp_f32_e32 v99, v99
	v_pk_add_f32 v[80:81], v[14:15], 0 op_sel_hi:[1,0]
	v_exp_f32_e32 v84, v84
	v_exp_f32_e32 v85, v85
	v_pk_add_f32 v[80:81], v[96:97], v[80:81]
	v_exp_f32_e32 v100, v100
	v_exp_f32_e32 v101, v101
	v_pk_add_f32 v[80:81], v[82:83], v[80:81]
	v_exp_f32_e32 v86, v86
	v_exp_f32_e32 v87, v87
	v_pk_add_f32 v[80:81], v[98:99], v[80:81]
	v_exp_f32_e32 v102, v102
	v_exp_f32_e32 v103, v103
	v_pk_add_f32 v[80:81], v[84:85], v[80:81]
	v_exp_f32_e32 v88, v88
	v_exp_f32_e32 v89, v89
	v_pk_add_f32 v[80:81], v[100:101], v[80:81]
	v_exp_f32_e32 v104, v104
	v_exp_f32_e32 v105, v105
	v_pk_add_f32 v[80:81], v[86:87], v[80:81]
	s_nop 0
	v_pk_add_f32 v[80:81], v[102:103], v[80:81]
	s_nop 0
	v_pk_add_f32 v[80:81], v[88:89], v[80:81]
	s_nop 0
	v_pk_add_f32 v[80:81], v[104:105], v[80:81]
	v_exp_f32_e32 v90, v90
	v_exp_f32_e32 v91, v91
	v_exp_f32_e32 v106, v106
	v_exp_f32_e32 v107, v107
	v_exp_f32_e32 v92, v92
	v_exp_f32_e32 v93, v93
	v_exp_f32_e32 v108, v108
	v_exp_f32_e32 v109, v109
	v_pk_add_f32 v[80:81], v[90:91], v[80:81]
	v_exp_f32_e32 v94, v94
	v_exp_f32_e32 v95, v95
	v_pk_add_f32 v[80:81], v[106:107], v[80:81]
	v_exp_f32_e32 v110, v110
	v_exp_f32_e32 v111, v111
	v_pk_add_f32 v[80:81], v[92:93], v[80:81]
	s_nop 0
	v_pk_add_f32 v[80:81], v[108:109], v[80:81]
	s_nop 0
	v_pk_add_f32 v[80:81], v[94:95], v[80:81]
	s_nop 0
	v_pk_add_f32 v[80:81], v[110:111], v[80:81]
	s_nop 0
	v_add_f32_e32 v80, v80, v81
	v_cmp_nge_f32_e32 vcc, 0x43800000, v230
	s_mov_b64 s[4:5], vcc
	v_cmp_nge_f32_e32 vcc, 0x43800000, v80
	s_or_b64 vcc, vcc, s[4:5]
	s_cbranch_vccnz .LB_slow1
	v_add_f32_e32 v245, v245, v230
	v_add_f32_e32 v236, v236, v80
	s_waitcnt lgkmcnt(3)
	v_mfma_f32_32x32x16_bf16 v[64:79], v[188:191], v[120:123], v[64:79]
	v_mfma_f32_32x32x16_bf16 v[64:79], v[180:183], v[124:127], v[64:79]
	v_cvt_pk_bf16_f32 v80, v14, v15
	v_cvt_pk_bf16_f32 v81, v82, v83
	v_cvt_pk_bf16_f32 v82, v84, v85
	v_cvt_pk_bf16_f32 v83, v86, v87
	v_cvt_pk_bf16_f32 v84, v96, v97
	v_cvt_pk_bf16_f32 v85, v98, v99
	s_waitcnt lgkmcnt(2)
	v_mfma_f32_32x32x16_bf16 v[64:79], v[10:13], v[112:115], v[64:79]
	v_cvt_pk_bf16_f32 v86, v100, v101
	v_cvt_pk_bf16_f32 v87, v102, v103
	v_cvt_pk_bf16_f32 v88, v88, v89
	v_cvt_pk_bf16_f32 v89, v90, v91
	v_cvt_pk_bf16_f32 v90, v92, v93
	v_cvt_pk_bf16_f32 v91, v94, v95
	v_cvt_pk_bf16_f32 v92, v104, v105
	v_cvt_pk_bf16_f32 v93, v106, v107
	v_cvt_pk_bf16_f32 v94, v108, v109
	v_cvt_pk_bf16_f32 v95, v110, v111
	s_waitcnt lgkmcnt(0)
	v_mfma_f32_32x32x16_bf16 v[64:79], v[184:187], v[116:119], v[64:79]
	v_mfma_f32_32x32x16_bf16 v[48:63], v[188:191], v[80:83], v[48:63]
	v_mfma_f32_32x32x16_bf16 v[48:63], v[180:183], v[88:91], v[48:63]
	v_mfma_f32_32x32x16_bf16 v[48:63], v[10:13], v[84:87], v[48:63]
	v_mfma_f32_32x32x16_bf16 v[48:63], v[184:187], v[92:95], v[48:63]
	ds_read_b64_tr_b16 v[12:13], v0 offset:28864
	ds_read_b64_tr_b16 v[96:97], v0 offset:30016
	ds_read_b64_tr_b16 v[98:99], v0 offset:31168
	ds_read_b64_tr_b16 v[100:101], v0 offset:32320
	ds_read_b64_tr_b16 v[10:11], v0 offset:27712
	ds_read_b64_tr_b16 v[102:103], v0 offset:33472
	ds_read_b64_tr_b16 v[104:105], v0 offset:34624
	ds_read_b64_tr_b16 v[106:107], v0 offset:35776
	s_setprio 1
	s_waitcnt lgkmcnt(3)
	v_mfma_f32_32x32x16_bf16 v[32:47], v[10:13], v[120:123], v[32:47]
	v_mfma_f32_32x32x16_bf16 v[16:31], v[10:13], v[80:83], v[16:31]
	v_mfma_f32_32x32x16_bf16 v[32:47], v[96:99], v[124:127], v[32:47]
	v_mfma_f32_32x32x16_bf16 v[16:31], v[96:99], v[88:91], v[16:31]
	s_waitcnt lgkmcnt(2)
	v_mfma_f32_32x32x16_bf16 v[32:47], v[100:103], v[112:115], v[32:47]
	v_mfma_f32_32x32x16_bf16 v[16:31], v[100:103], v[84:87], v[16:31]
	s_waitcnt lgkmcnt(0)
	v_mfma_f32_32x32x16_bf16 v[32:47], v[104:107], v[116:119], v[32:47]
	v_mfma_f32_32x32x16_bf16 v[16:31], v[104:107], v[92:95], v[16:31]
	s_setprio 0
; #define LAS __attribute__((address_space(3)))
; template <int DQK, int NMAP>
; DI void att_qk(const LAS unsigned char* Kb, int r, int h, const bf16x8 (&qfm)[DQK / NMAP / 16], int mp, f32x16 (&S)[2]) {
;     constexpr int DQM = DQK / NMAP, NKS = DQM / 16, KP = DQK * 2 + 16, CH = (NKS > 4) ? 3 : NKS;
;     const LAS unsigned char* kp = Kb + r * KP + (mp * DQM + 8 * h) * 2;
;     const f32x16 z = {0.f, 0.f, 0.f, 0.f, 0.f, 0.f, 0.f, 0.f, 0.f, 0.f, 0.f, 0.f, 0.f, 0.f, 0.f, 0.f};
; #pragma unroll
;     for (int c = 0; c < NKS / CH; ++c) {
;         bf16x8 kf[2 * CH];
; #pragma unroll
;         for (int s = 0; s < CH; ++s) { kf[2 * s] = *(const LAS bf16x8*)(kp + 32 * (c * CH + s)); kf[2 * s + 1] = *(const LAS bf16x8*)(kp + 32 * KP + 32 * (c * CH + s)); }
;         __builtin_amdgcn_sched_barrier(0);
;         __builtin_amdgcn_s_setprio(1);
; #pragma unroll
;         for (int s = 0; s < CH; ++s) {
;             if (c == 0 && s == 0) { S[0] = __builtin_amdgcn_mfma_f32_32x32x16_bf16(kf[0], qfm[0], z, 0, 0, 0); S[1] = __builtin_amdgcn_mfma_f32_32x32x16_bf16(kf[1], qfm[0], z, 0, 0, 0); }
;             else { S[0] = __builtin_amdgcn_mfma_f32_32x32x16_bf16(kf[2 * s], qfm[c * CH + s], S[0], 0, 0, 0); S[1] = __builtin_amdgcn_mfma_f32_32x32x16_bf16(kf[2 * s + 1], qfm[c * CH + s], S[1], 0, 0, 0); }
;         }
;         __builtin_amdgcn_s_setprio(0);
;         __builtin_amdgcn_sched_barrier(0);
;     }
; }
.LBB0_586:
	s_bitcmp1_b32 s12, 0
	s_cselect_b32 s3, 0x2400, 0
	s_add_i32 s3, s3, 0
	s_add_i32 s4, s12, 5
	s_cmp_lt_u32 s4, s9
	s_cselect_b32 s4, s4, s8
	s_lshl_b32 s5, s4, 6
	s_add_i32 s5, s5, s0
	s_cmp_lt_u32 s4, 4
	s_cselect_b32 s4, s1, s5
	s_ashr_i32 s5, s4, 31
	v_lshl_add_u64 v[10:11], s[4:5], 0, v[200:201]
	v_lshlrev_b64 v[10:11], 9, v[10:11]
	v_add3_u32 v0, s3, v239, v240
	v_lshl_add_u64 v[10:11], v[206:207], 0, v[10:11]
	s_waitcnt vmcnt(5)
	ds_write_b128 v0, v[176:179]
	s_waitcnt vmcnt(4)
	ds_write_b128 v242, v[172:175] offset:36864
	s_waitcnt lgkmcnt(0)
	s_barrier
	global_load_dwordx4 v[176:179], v[10:11], off
	v_lshl_add_u64 v[10:11], s[4:5], 0, v[202:203]
	v_mad_u64_u32 v[12:13], s[4:5], v10, s78, v[208:209]
	v_mad_i32_i24 v13, v11, s78, v13
	global_load_dwordx4 v[172:175], v[12:13], off
	s_cmp_ge_u32 s12, s11
	s_cbranch_scc1 .LBB0_592
	v_add_u32_e32 v0, s3, v243
	v_add_u32_e32 v0, v0, v204
	ds_read_b128 v[10:13], v0
	ds_read_b128 v[80:83], v0 offset:32
	ds_read_b128 v[84:87], v0 offset:4608
	ds_read_b128 v[88:91], v0 offset:4640
	ds_read_b128 v[188:191], v0 offset:128
	ds_read_b128 v[246:249], v0 offset:4736
	v_mov_b32_e32 v230, 0
	s_mov_b64 exec, 0xffffffff
	v_cvt_pk_bf16_f32 v230, v212, 0
	s_mov_b64 exec, -1
	s_setprio 1
	s_waitcnt lgkmcnt(5)
	v_mfma_f32_32x32x16_bf16 v[112:127], v[10:13], v[156:159], 0
	s_waitcnt lgkmcnt(3)
	v_mfma_f32_32x32x16_bf16 v[128:143], v[84:87], v[156:159], 0
	v_mfma_f32_32x32x16_bf16 v[112:127], v[80:83], v[160:163], v[112:127]
	s_waitcnt lgkmcnt(2)
	v_mfma_f32_32x32x16_bf16 v[128:143], v[88:91], v[160:163], v[128:143]
	s_waitcnt lgkmcnt(1)
	v_mfma_f32_32x32x16_bf16 v[112:127], v[188:191], v[230:233], v[112:127]
	s_waitcnt lgkmcnt(0)
	v_mfma_f32_32x32x16_bf16 v[128:143], v[246:249], v[230:233], v[128:143]
	s_setprio 0
	v_mov_b32_e32 v230, 0
	s_mov_b64 exec, 0xffffffff
	v_cvt_pk_bf16_f32 v230, v210, 0
	s_mov_b64 exec, -1
	ds_read_b128 v[10:13], v0 offset:64
	ds_read_b128 v[180:183], v0 offset:96
	ds_read_b128 v[96:99], v0 offset:4672
	ds_read_b128 v[184:187], v0 offset:4704
	s_setprio 1
	s_waitcnt lgkmcnt(3)
	v_mfma_f32_32x32x16_bf16 v[80:95], v[10:13], v[164:167], 0
	s_waitcnt lgkmcnt(1)
	v_mfma_f32_32x32x16_bf16 v[96:111], v[96:99], v[164:167], 0
	v_mfma_f32_32x32x16_bf16 v[80:95], v[180:183], v[168:171], v[80:95]
	s_waitcnt lgkmcnt(0)
	v_mfma_f32_32x32x16_bf16 v[96:111], v[184:187], v[168:171], v[96:111]
	v_mfma_f32_32x32x16_bf16 v[80:95], v[188:191], v[230:233], v[80:95]
	v_mfma_f32_32x32x16_bf16 v[96:111], v[246:249], v[230:233], v[96:111]
	s_setprio 0
	v_add_u32_e32 v0, v238, v237
	ds_read_b64_tr_b16 v[188:189], v0 offset:36864
	ds_read_b64_tr_b16 v[190:191], v0 offset:38016
	ds_read_b64_tr_b16 v[184:185], v0 offset:39168
	ds_read_b64_tr_b16 v[186:187], v0 offset:40320
	ds_read_b64_tr_b16 v[180:181], v0 offset:41472
	ds_read_b64_tr_b16 v[182:183], v0 offset:42624
	ds_read_b64_tr_b16 v[10:11], v0 offset:43776
	ds_read_b64_tr_b16 v[12:13], v0 offset:44928
	s_nop 1
	v_exp_f32_e32 v14, v112
	v_exp_f32_e32 v15, v113
	v_exp_f32_e32 v112, v128
	v_exp_f32_e32 v113, v129
	v_exp_f32_e32 v114, v114
	v_exp_f32_e32 v115, v115
	v_exp_f32_e32 v128, v130
	v_exp_f32_e32 v129, v131
	v_pk_add_f32 v[130:131], v[14:15], 0 op_sel_hi:[1,0]
	v_exp_f32_e32 v116, v116
	v_exp_f32_e32 v117, v117
	v_pk_add_f32 v[130:131], v[112:113], v[130:131]
	v_exp_f32_e32 v132, v132
	v_exp_f32_e32 v133, v133
	v_pk_add_f32 v[130:131], v[114:115], v[130:131]
	v_exp_f32_e32 v118, v118
	v_exp_f32_e32 v119, v119
	v_pk_add_f32 v[130:131], v[128:129], v[130:131]
	v_exp_f32_e32 v134, v134
	v_exp_f32_e32 v135, v135
	v_pk_add_f32 v[130:131], v[116:117], v[130:131]
	v_exp_f32_e32 v246, v120
	v_exp_f32_e32 v247, v121
	v_pk_add_f32 v[130:131], v[132:133], v[130:131]
	v_exp_f32_e32 v136, v136
	v_exp_f32_e32 v137, v137
	v_pk_add_f32 v[130:131], v[118:119], v[130:131]
	v_exp_f32_e32 v248, v138
	v_exp_f32_e32 v138, v122
	v_exp_f32_e32 v249, v139
	v_exp_f32_e32 v139, v123
	v_pk_add_f32 v[130:131], v[134:135], v[130:131]
	v_pk_add_f32 v[120:121], v[246:247], v[130:131]
	v_exp_f32_e32 v130, v124
	v_exp_f32_e32 v131, v125
	v_pk_add_f32 v[120:121], v[136:137], v[120:121]
	v_exp_f32_e32 v140, v140
	v_exp_f32_e32 v141, v141
	v_pk_add_f32 v[120:121], v[138:139], v[120:121]
	v_exp_f32_e32 v250, v142
	v_exp_f32_e32 v142, v126
	v_exp_f32_e32 v251, v143
	v_exp_f32_e32 v143, v127
	v_pk_add_f32 v[120:121], v[248:249], v[120:121]
	v_pk_add_f32 v[120:121], v[130:131], v[120:121]
	v_cvt_pk_bf16_f32 v122, v116, v117
	v_pk_add_f32 v[120:121], v[140:141], v[120:121]
	v_cvt_pk_bf16_f32 v123, v118, v119
	v_pk_add_f32 v[120:121], v[142:143], v[120:121]
	v_cvt_pk_bf16_f32 v112, v112, v113
	v_pk_add_f32 v[120:121], v[250:251], v[120:121]
	v_cvt_pk_bf16_f32 v113, v128, v129
	v_add_f32_e32 v120, v120, v121
	v_mov_b32_e32 v230, v120
	v_cvt_pk_bf16_f32 v120, v14, v15
	v_cvt_pk_bf16_f32 v121, v114, v115
	v_cvt_pk_bf16_f32 v114, v132, v133
	v_cvt_pk_bf16_f32 v115, v134, v135
	v_cvt_pk_bf16_f32 v124, v246, v247
	v_cvt_pk_bf16_f32 v125, v138, v139
	v_cvt_pk_bf16_f32 v126, v130, v131
	v_cvt_pk_bf16_f32 v127, v142, v143
	v_cvt_pk_bf16_f32 v116, v136, v137
	v_cvt_pk_bf16_f32 v117, v248, v249
	v_cvt_pk_bf16_f32 v118, v140, v141
	v_cvt_pk_bf16_f32 v119, v250, v251
	v_exp_f32_e32 v14, v80
	v_exp_f32_e32 v15, v81
	v_exp_f32_e32 v96, v96
	v_exp_f32_e32 v97, v97
	v_exp_f32_e32 v82, v82
	v_exp_f32_e32 v83, v83
	v_exp_f32_e32 v98, v98
	v_exp_f32_e32 v99, v99
	v_pk_add_f32 v[80:81], v[14:15], 0 op_sel_hi:[1,0]
	v_exp_f32_e32 v84, v84
	v_exp_f32_e32 v85, v85
	v_pk_add_f32 v[80:81], v[96:97], v[80:81]
	v_exp_f32_e32 v100, v100
	v_exp_f32_e32 v101, v101
	v_pk_add_f32 v[80:81], v[82:83], v[80:81]
	v_exp_f32_e32 v86, v86
	v_exp_f32_e32 v87, v87
	v_pk_add_f32 v[80:81], v[98:99], v[80:81]
	v_exp_f32_e32 v102, v102
	v_exp_f32_e32 v103, v103
	v_pk_add_f32 v[80:81], v[84:85], v[80:81]
	v_exp_f32_e32 v88, v88
	v_exp_f32_e32 v89, v89
	v_pk_add_f32 v[80:81], v[100:101], v[80:81]
	v_exp_f32_e32 v104, v104
	v_exp_f32_e32 v105, v105
	v_pk_add_f32 v[80:81], v[86:87], v[80:81]
	s_nop 0
	v_pk_add_f32 v[80:81], v[102:103], v[80:81]
	s_nop 0
	v_pk_add_f32 v[80:81], v[88:89], v[80:81]
	s_nop 0
	v_pk_add_f32 v[80:81], v[104:105], v[80:81]
	v_exp_f32_e32 v90, v90
	v_exp_f32_e32 v91, v91
	v_exp_f32_e32 v106, v106
	v_exp_f32_e32 v107, v107
	v_exp_f32_e32 v92, v92
	v_exp_f32_e32 v93, v93
	v_exp_f32_e32 v108, v108
	v_exp_f32_e32 v109, v109
	v_pk_add_f32 v[80:81], v[90:91], v[80:81]
	v_exp_f32_e32 v94, v94
	v_exp_f32_e32 v95, v95
	v_pk_add_f32 v[80:81], v[106:107], v[80:81]
	v_exp_f32_e32 v110, v110
	v_exp_f32_e32 v111, v111
	v_pk_add_f32 v[80:81], v[92:93], v[80:81]
	s_nop 0
	v_pk_add_f32 v[80:81], v[108:109], v[80:81]
	s_nop 0
	v_pk_add_f32 v[80:81], v[94:95], v[80:81]
	s_nop 0
	v_pk_add_f32 v[80:81], v[110:111], v[80:81]
	s_nop 0
	v_add_f32_e32 v80, v80, v81
	v_cmp_nge_f32_e32 vcc, 0x43800000, v230
	s_mov_b64 s[4:5], vcc
	v_cmp_nge_f32_e32 vcc, 0x43800000, v80
	s_or_b64 vcc, vcc, s[4:5]
	s_cbranch_vccnz .LB_slow2
	v_add_f32_e32 v245, v245, v230
	v_add_f32_e32 v236, v236, v80
	s_waitcnt lgkmcnt(6)
	v_mfma_f32_32x32x16_bf16 v[64:79], v[188:191], v[120:123], v[64:79]
	s_waitcnt lgkmcnt(4)
	v_mfma_f32_32x32x16_bf16 v[64:79], v[184:187], v[124:127], v[64:79]
	v_cvt_pk_bf16_f32 v80, v14, v15
	v_cvt_pk_bf16_f32 v81, v82, v83
	v_cvt_pk_bf16_f32 v82, v84, v85
	v_cvt_pk_bf16_f32 v83, v86, v87
	v_cvt_pk_bf16_f32 v84, v96, v97
	v_cvt_pk_bf16_f32 v85, v98, v99
	s_waitcnt lgkmcnt(2)
	v_mfma_f32_32x32x16_bf16 v[64:79], v[180:183], v[112:115], v[64:79]
	v_cvt_pk_bf16_f32 v86, v100, v101
	v_cvt_pk_bf16_f32 v87, v102, v103
	v_cvt_pk_bf16_f32 v88, v88, v89
	v_cvt_pk_bf16_f32 v89, v90, v91
	v_cvt_pk_bf16_f32 v90, v92, v93
	v_cvt_pk_bf16_f32 v91, v94, v95
	v_cvt_pk_bf16_f32 v92, v104, v105
	v_cvt_pk_bf16_f32 v93, v106, v107
	v_cvt_pk_bf16_f32 v94, v108, v109
	v_cvt_pk_bf16_f32 v95, v110, v111
	s_waitcnt lgkmcnt(0)
	v_mfma_f32_32x32x16_bf16 v[64:79], v[10:13], v[116:119], v[64:79]
	v_mfma_f32_32x32x16_bf16 v[48:63], v[188:191], v[80:83], v[48:63]
	v_mfma_f32_32x32x16_bf16 v[48:63], v[184:187], v[88:91], v[48:63]
	v_mfma_f32_32x32x16_bf16 v[48:63], v[180:183], v[84:87], v[48:63]
	v_mfma_f32_32x32x16_bf16 v[48:63], v[10:13], v[92:95], v[48:63]
	ds_read_b64_tr_b16 v[10:11], v0 offset:36928
	ds_read_b64_tr_b16 v[12:13], v0 offset:38080
	ds_read_b64_tr_b16 v[96:97], v0 offset:39232
	ds_read_b64_tr_b16 v[98:99], v0 offset:40384
	ds_read_b64_tr_b16 v[100:101], v0 offset:41536
	ds_read_b64_tr_b16 v[102:103], v0 offset:42688
	ds_read_b64_tr_b16 v[104:105], v0 offset:43840
	ds_read_b64_tr_b16 v[106:107], v0 offset:44992
	s_setprio 1
	s_waitcnt lgkmcnt(6)
	v_mfma_f32_32x32x16_bf16 v[32:47], v[10:13], v[120:123], v[32:47]
	v_mfma_f32_32x32x16_bf16 v[16:31], v[10:13], v[80:83], v[16:31]
	s_waitcnt lgkmcnt(4)
	v_mfma_f32_32x32x16_bf16 v[32:47], v[96:99], v[124:127], v[32:47]
	v_mfma_f32_32x32x16_bf16 v[16:31], v[96:99], v[88:91], v[16:31]
	s_waitcnt lgkmcnt(2)
	v_mfma_f32_32x32x16_bf16 v[32:47], v[100:103], v[112:115], v[32:47]
	v_mfma_f32_32x32x16_bf16 v[16:31], v[100:103], v[84:87], v[16:31]
	s_waitcnt lgkmcnt(0)
	v_mfma_f32_32x32x16_bf16 v[32:47], v[104:107], v[116:119], v[32:47]
	v_mfma_f32_32x32x16_bf16 v[16:31], v[104:107], v[92:95], v[16:31]
	s_setprio 0

; #define LAS __attribute__((address_space(3)))
; DI float fast_exp2(float x) { return __builtin_amdgcn_exp2f(x); }
; template <int DQK, int NMAP>
; DI void att_qk(const LAS unsigned char* Kb, int r, int h, const bf16x8 (&qfm)[DQK / NMAP / 16], int mp, f32x16 (&S)[2]) {
;     ...
;         bf16x8 kf[2 * CH];
; #pragma unroll
;         for (int s = 0; s < CH; ++s) { kf[2 * s] = *(const LAS bf16x8*)(kp + 32 * (c * CH + s)); kf[2 * s + 1] = *(const LAS bf16x8*)(kp + 32 * KP + 32 * (c * CH + s)); }
;         __builtin_amdgcn_sched_barrier(0);
;         __builtin_amdgcn_s_setprio(1);
; #pragma unroll
;         for (int s = 0; s < CH; ++s) {
;             if (c == 0 && s == 0) { S[0] = __builtin_amdgcn_mfma_f32_32x32x16_bf16(kf[0], qfm[0], z, 0, 0, 0); S[1] = __builtin_amdgcn_mfma_f32_32x32x16_bf16(kf[1], qfm[0], z, 0, 0, 0); }
;             else { S[0] = __builtin_amdgcn_mfma_f32_32x32x16_bf16(kf[2 * s], qfm[c * CH + s], S[0], 0, 0, 0); S[1] = __builtin_amdgcn_mfma_f32_32x32x16_bf16(kf[2 * s + 1], qfm[c * CH + s], S[1], 0, 0, 0); }
;         }
;         __builtin_amdgcn_s_setprio(0);
;         __builtin_amdgcn_sched_barrier(0);
; template <int MODE>
; DI void att_sm_head(f32x16 (&S)[2], float& mrefm, float& lrunm, f32x16 (&om)[2], bool latent, const MaskP& mk, int h) {
;     ...
;         float ma = fmaxf(fmaxf(s0[0], s0[1]), s0[2]), mb = fmaxf(fmaxf(s1[0], s1[1]), s1[2]);
; #pragma unroll
;         for (int i = 3; i < 15; i += 2) { ma = fmaxf(fmaxf(ma, s0[i]), s0[i + 1]); mb = fmaxf(fmaxf(mb, s1[i]), s1[i + 1]); }
;         ma = fmaxf(fmaxf(ma, s0[15]), fmaxf(mb, s1[15]));
;         { auto rr = __builtin_amdgcn_permlane32_swap(__float_as_uint(ma), __float_as_uint(ma), false, false); ma = fmaxf(__uint_as_float(rr[0]), __uint_as_float(rr[1])); }
;         const bool uninit = mrefm < -1e29f;
;         const bool need = uninit || (ma - mrefm > 8.0f);
;         if (__any(need)) {
;             const float mnew = need ? ma : mrefm;
;             const float f = uninit ? 1.0f : fast_exp2(mrefm - mnew);
;             mrefm = mnew; lrunm *= f;
; #pragma unroll
;             for (int e = 0; e < 2; ++e)
; #pragma unroll
;                 for (int i = 0; i < 16; ++i) om[e][i] *= f;
;         }
.LB_slow0:
	s_bitcmp1_b32 s12, 0
	s_cselect_b32 s3, 0x2400, 0
	v_add_u32_e32 v0, s3, v244
	ds_read_b128 v[10:13], v0
	ds_read_b128 v[80:83], v0 offset:32
	ds_read_b128 v[84:87], v0 offset:4608
	ds_read_b128 v[88:91], v0 offset:4640
	s_setprio 1
	s_waitcnt lgkmcnt(3)
	v_mfma_f32_32x32x16_bf16 v[112:127], v[10:13], v[156:159], 0
	s_waitcnt lgkmcnt(1)
	v_mfma_f32_32x32x16_bf16 v[128:143], v[84:87], v[156:159], 0
	v_mfma_f32_32x32x16_bf16 v[112:127], v[80:83], v[160:163], v[112:127]
	s_waitcnt lgkmcnt(0)
	v_mfma_f32_32x32x16_bf16 v[128:143], v[88:91], v[160:163], v[128:143]
	s_setprio 0
	s_nop 10
	v_max_f32_e32 v11, v129, v129
	v_max_f32_e32 v12, v128, v128
	v_max_f32_e32 v11, v12, v11
	v_max3_f32 v10, v112, v113, v114
	v_max3_f32 v11, v11, v130, v131
	v_max3_f32 v10, v10, v115, v116
	v_max3_f32 v11, v11, v132, v133
	v_max3_f32 v10, v10, v117, v118
	v_max3_f32 v11, v11, v134, v135
	v_max3_f32 v10, v10, v119, v120
	v_max3_f32 v11, v11, v136, v137
	v_max3_f32 v10, v10, v121, v122
	v_max3_f32 v11, v11, v138, v139
	v_max3_f32 v10, v10, v123, v124
	v_max3_f32 v11, v11, v140, v141
	v_max3_f32 v10, v10, v125, v126
	v_max3_f32 v11, v11, v142, v143
	v_max3_f32 v10, v10, v127, v11
	v_mov_b32_e32 v11, v10
	s_nop 1
	v_permlane32_swap_b32_e32 v10, v11
	v_max_f32_e32 v11, v11, v11
	v_max_f32_e32 v10, v10, v10
	v_max_f32_e32 v10, v10, v11
	v_cvt_pk_bf16_f32 v10, v10, v10
	v_lshlrev_b32_e32 v10, 16, v10
	v_sub_f32_e32 v11, v10, v212
	v_cmp_gt_f32_e64 s[4:5], s22, v212
	v_cmp_lt_f32_e32 vcc, s23, v11
	s_or_b64 vcc, s[4:5], vcc
	s_cbranch_vccz .LB_rescA0
	v_cndmask_b32_e32 v11, v212, v10, vcc
	v_sub_f32_e32 v10, v212, v11
	v_exp_f32_e32 v10, v10
	v_mov_b32_e32 v212, v11
	v_cndmask_b32_e64 v10, v10, 1.0, s[4:5]
	v_mul_f32_e32 v245, v245, v10
	v_pk_mul_f32 v[78:79], v[78:79], v[10:11] op_sel_hi:[1,0]
	v_pk_mul_f32 v[76:77], v[76:77], v[10:11] op_sel_hi:[1,0]
	v_pk_mul_f32 v[74:75], v[74:75], v[10:11] op_sel_hi:[1,0]
	v_pk_mul_f32 v[72:73], v[72:73], v[10:11] op_sel_hi:[1,0]
	v_pk_mul_f32 v[70:71], v[70:71], v[10:11] op_sel_hi:[1,0]
	v_pk_mul_f32 v[68:69], v[68:69], v[10:11] op_sel_hi:[1,0]
	v_pk_mul_f32 v[66:67], v[66:67], v[10:11] op_sel_hi:[1,0]
	v_pk_mul_f32 v[64:65], v[64:65], v[10:11] op_sel_hi:[1,0]
	v_pk_mul_f32 v[46:47], v[46:47], v[10:11] op_sel_hi:[1,0]
	v_pk_mul_f32 v[44:45], v[44:45], v[10:11] op_sel_hi:[1,0]
	v_pk_mul_f32 v[42:43], v[42:43], v[10:11] op_sel_hi:[1,0]
	v_pk_mul_f32 v[40:41], v[40:41], v[10:11] op_sel_hi:[1,0]
	v_pk_mul_f32 v[38:39], v[38:39], v[10:11] op_sel_hi:[1,0]
	v_pk_mul_f32 v[36:37], v[36:37], v[10:11] op_sel_hi:[1,0]
	v_pk_mul_f32 v[34:35], v[34:35], v[10:11] op_sel_hi:[1,0]
	v_pk_mul_f32 v[32:33], v[32:33], v[10:11] op_sel_hi:[1,0]
.LB_rescA0:
	ds_read_b128 v[10:13], v0 offset:64
	ds_read_b128 v[180:183], v0 offset:96
	ds_read_b128 v[96:99], v0 offset:4672
	ds_read_b128 v[184:187], v0 offset:4704
	s_setprio 1
	s_waitcnt lgkmcnt(3)
	v_mfma_f32_32x32x16_bf16 v[80:95], v[10:13], v[164:167], 0
	s_waitcnt lgkmcnt(1)
	v_mfma_f32_32x32x16_bf16 v[96:111], v[96:99], v[164:167], 0
	v_mfma_f32_32x32x16_bf16 v[80:95], v[180:183], v[168:171], v[80:95]
	s_waitcnt lgkmcnt(0)
	v_mfma_f32_32x32x16_bf16 v[96:111], v[184:187], v[168:171], v[96:111]
	s_setprio 0
	v_add_u32_e32 v0, v238, v237
	ds_read_b64_tr_b16 v[188:189], v0 offset:18432
	ds_read_b64_tr_b16 v[190:191], v0 offset:19584
	ds_read_b64_tr_b16 v[184:185], v0 offset:20736
	ds_read_b64_tr_b16 v[186:187], v0 offset:21888
	ds_read_b64_tr_b16 v[180:181], v0 offset:23040
	ds_read_b64_tr_b16 v[182:183], v0 offset:24192
	ds_read_b64_tr_b16 v[10:11], v0 offset:25344
	ds_read_b64_tr_b16 v[12:13], v0 offset:26496
	s_nop 1
	v_max_f32_e32 v15, v97, v97
	v_max_f32_e32 v230, v96, v96
	v_max_f32_e32 v15, v230, v15
	v_max3_f32 v14, v80, v81, v82
	v_max3_f32 v15, v15, v98, v99
	v_max3_f32 v14, v14, v83, v84
	v_max3_f32 v15, v15, v100, v101
	v_max3_f32 v14, v14, v85, v86
	v_max3_f32 v15, v15, v102, v103
	v_max3_f32 v14, v14, v87, v88
	v_max3_f32 v15, v15, v104, v105
	v_max3_f32 v14, v14, v89, v90
	v_max3_f32 v15, v15, v106, v107
	v_max3_f32 v14, v14, v91, v92
	v_max3_f32 v15, v15, v108, v109
	v_max3_f32 v14, v14, v93, v94
	v_max3_f32 v15, v15, v110, v111
	v_max3_f32 v14, v14, v95, v15
	v_mov_b32_e32 v15, v14
	s_nop 1
	v_permlane32_swap_b32_e32 v14, v15
	v_max_f32_e32 v15, v15, v15
	v_max_f32_e32 v14, v14, v14
	v_max_f32_e32 v14, v14, v15
	v_cvt_pk_bf16_f32 v14, v14, v14
	v_lshlrev_b32_e32 v14, 16, v14
	v_sub_f32_e32 v15, v14, v210
	v_cmp_gt_f32_e64 s[4:5], s22, v210
	v_cmp_lt_f32_e32 vcc, s23, v15
	s_or_b64 vcc, s[4:5], vcc
	s_cbranch_vccz .LB_rescB0
	v_cndmask_b32_e32 v15, v210, v14, vcc
	v_sub_f32_e32 v14, v210, v15
	v_exp_f32_e32 v14, v14
	v_mov_b32_e32 v210, v15
	v_cndmask_b32_e64 v14, v14, 1.0, s[4:5]
	v_mul_f32_e32 v236, v236, v14
	v_pk_mul_f32 v[62:63], v[62:63], v[14:15] op_sel_hi:[1,0]
	v_pk_mul_f32 v[60:61], v[60:61], v[14:15] op_sel_hi:[1,0]
	v_pk_mul_f32 v[58:59], v[58:59], v[14:15] op_sel_hi:[1,0]
	v_pk_mul_f32 v[56:57], v[56:57], v[14:15] op_sel_hi:[1,0]
	v_pk_mul_f32 v[54:55], v[54:55], v[14:15] op_sel_hi:[1,0]
	v_pk_mul_f32 v[52:53], v[52:53], v[14:15] op_sel_hi:[1,0]
	v_pk_mul_f32 v[50:51], v[50:51], v[14:15] op_sel_hi:[1,0]
	v_pk_mul_f32 v[48:49], v[48:49], v[14:15] op_sel_hi:[1,0]
	v_pk_mul_f32 v[30:31], v[30:31], v[14:15] op_sel_hi:[1,0]
	v_pk_mul_f32 v[28:29], v[28:29], v[14:15] op_sel_hi:[1,0]
	v_pk_mul_f32 v[26:27], v[26:27], v[14:15] op_sel_hi:[1,0]
	v_pk_mul_f32 v[24:25], v[24:25], v[14:15] op_sel_hi:[1,0]
	v_pk_mul_f32 v[22:23], v[22:23], v[14:15] op_sel_hi:[1,0]
	v_pk_mul_f32 v[20:21], v[20:21], v[14:15] op_sel_hi:[1,0]
	v_pk_mul_f32 v[18:19], v[18:19], v[14:15] op_sel_hi:[1,0]
	v_pk_mul_f32 v[16:17], v[16:17], v[14:15] op_sel_hi:[1,0]

; #define LAS __attribute__((address_space(3)))
; DI float fast_exp2(float x) { return __builtin_amdgcn_exp2f(x); }
; template <int DQK, int NMAP>
; DI void att_qk(const LAS unsigned char* Kb, int r, int h, const bf16x8 (&qfm)[DQK / NMAP / 16], int mp, f32x16 (&S)[2]) {
;     ...
;         bf16x8 kf[2 * CH];
; #pragma unroll
;         for (int s = 0; s < CH; ++s) { kf[2 * s] = *(const LAS bf16x8*)(kp + 32 * (c * CH + s)); kf[2 * s + 1] = *(const LAS bf16x8*)(kp + 32 * KP + 32 * (c * CH + s)); }
;         __builtin_amdgcn_sched_barrier(0);
;         __builtin_amdgcn_s_setprio(1);
; #pragma unroll
;         for (int s = 0; s < CH; ++s) {
;             if (c == 0 && s == 0) { S[0] = __builtin_amdgcn_mfma_f32_32x32x16_bf16(kf[0], qfm[0], z, 0, 0, 0); S[1] = __builtin_amdgcn_mfma_f32_32x32x16_bf16(kf[1], qfm[0], z, 0, 0, 0); }
;             else { S[0] = __builtin_amdgcn_mfma_f32_32x32x16_bf16(kf[2 * s], qfm[c * CH + s], S[0], 0, 0, 0); S[1] = __builtin_amdgcn_mfma_f32_32x32x16_bf16(kf[2 * s + 1], qfm[c * CH + s], S[1], 0, 0, 0); }
;         }
;         __builtin_amdgcn_s_setprio(0);
;         __builtin_amdgcn_sched_barrier(0);
; template <int MODE>
; DI void att_sm_head(f32x16 (&S)[2], float& mrefm, float& lrunm, f32x16 (&om)[2], bool latent, const MaskP& mk, int h) {
;     ...
;         float ma = fmaxf(fmaxf(s0[0], s0[1]), s0[2]), mb = fmaxf(fmaxf(s1[0], s1[1]), s1[2]);
; #pragma unroll
;         for (int i = 3; i < 15; i += 2) { ma = fmaxf(fmaxf(ma, s0[i]), s0[i + 1]); mb = fmaxf(fmaxf(mb, s1[i]), s1[i + 1]); }
;         ma = fmaxf(fmaxf(ma, s0[15]), fmaxf(mb, s1[15]));
;         { auto rr = __builtin_amdgcn_permlane32_swap(__float_as_uint(ma), __float_as_uint(ma), false, false); ma = fmaxf(__uint_as_float(rr[0]), __uint_as_float(rr[1])); }
;         const bool uninit = mrefm < -1e29f;
;         const bool need = uninit || (ma - mrefm > 8.0f);
;         if (__any(need)) {
;             const float mnew = need ? ma : mrefm;
;             const float f = uninit ? 1.0f : fast_exp2(mrefm - mnew);
;             mrefm = mnew; lrunm *= f;
; #pragma unroll
;             for (int e = 0; e < 2; ++e)
; #pragma unroll
;                 for (int i = 0; i < 16; ++i) om[e][i] *= f;
;         }
.LB_slow1:
	v_add_u32_e32 v0, s3, v243
	v_add_u32_e32 v0, v0, v204
	ds_read_b128 v[10:13], v0
	ds_read_b128 v[80:83], v0 offset:32
	ds_read_b128 v[84:87], v0 offset:4608
	ds_read_b128 v[88:91], v0 offset:4640
	s_setprio 1
	s_waitcnt lgkmcnt(3)
	v_mfma_f32_32x32x16_bf16 v[112:127], v[10:13], v[156:159], 0
	s_waitcnt lgkmcnt(1)
	v_mfma_f32_32x32x16_bf16 v[128:143], v[84:87], v[156:159], 0
	v_mfma_f32_32x32x16_bf16 v[112:127], v[80:83], v[160:163], v[112:127]
	s_waitcnt lgkmcnt(0)
	v_mfma_f32_32x32x16_bf16 v[128:143], v[88:91], v[160:163], v[128:143]
	s_setprio 0
	s_nop 10
	v_max_f32_e32 v11, v129, v129
	v_max_f32_e32 v12, v128, v128
	v_max_f32_e32 v11, v12, v11
	v_max3_f32 v10, v112, v113, v114
	v_max3_f32 v11, v11, v130, v131
	v_max3_f32 v10, v10, v115, v116
	v_max3_f32 v11, v11, v132, v133
	v_max3_f32 v10, v10, v117, v118
	v_max3_f32 v11, v11, v134, v135
	v_max3_f32 v10, v10, v119, v120
	v_max3_f32 v11, v11, v136, v137
	v_max3_f32 v10, v10, v121, v122
	v_max3_f32 v11, v11, v138, v139
	v_max3_f32 v10, v10, v123, v124
	v_max3_f32 v11, v11, v140, v141
	v_max3_f32 v10, v10, v125, v126
	v_max3_f32 v11, v11, v142, v143
	v_max3_f32 v10, v10, v127, v11
	v_mov_b32_e32 v11, v10
	s_nop 1
	v_permlane32_swap_b32_e32 v10, v11
	v_max_f32_e32 v11, v11, v11
	v_max_f32_e32 v10, v10, v10
	v_max_f32_e32 v10, v10, v11
	v_cvt_pk_bf16_f32 v10, v10, v10
	v_lshlrev_b32_e32 v10, 16, v10
	v_sub_f32_e32 v11, v10, v212
	v_cmp_gt_f32_e64 s[4:5], s22, v212
	v_cmp_lt_f32_e32 vcc, s23, v11
	s_or_b64 vcc, s[4:5], vcc
	s_cbranch_vccz .LB_rescA1
	v_cndmask_b32_e32 v11, v212, v10, vcc
	v_sub_f32_e32 v10, v212, v11
	v_exp_f32_e32 v10, v10
	v_mov_b32_e32 v212, v11
	v_cndmask_b32_e64 v10, v10, 1.0, s[4:5]
	v_mul_f32_e32 v245, v245, v10
	v_pk_mul_f32 v[78:79], v[78:79], v[10:11] op_sel_hi:[1,0]
	v_pk_mul_f32 v[76:77], v[76:77], v[10:11] op_sel_hi:[1,0]
	v_pk_mul_f32 v[74:75], v[74:75], v[10:11] op_sel_hi:[1,0]
	v_pk_mul_f32 v[72:73], v[72:73], v[10:11] op_sel_hi:[1,0]
	v_pk_mul_f32 v[70:71], v[70:71], v[10:11] op_sel_hi:[1,0]
	v_pk_mul_f32 v[68:69], v[68:69], v[10:11] op_sel_hi:[1,0]
	v_pk_mul_f32 v[66:67], v[66:67], v[10:11] op_sel_hi:[1,0]
	v_pk_mul_f32 v[64:65], v[64:65], v[10:11] op_sel_hi:[1,0]
	v_pk_mul_f32 v[46:47], v[46:47], v[10:11] op_sel_hi:[1,0]
	v_pk_mul_f32 v[44:45], v[44:45], v[10:11] op_sel_hi:[1,0]
	v_pk_mul_f32 v[42:43], v[42:43], v[10:11] op_sel_hi:[1,0]
	v_pk_mul_f32 v[40:41], v[40:41], v[10:11] op_sel_hi:[1,0]
	v_pk_mul_f32 v[38:39], v[38:39], v[10:11] op_sel_hi:[1,0]
	v_pk_mul_f32 v[36:37], v[36:37], v[10:11] op_sel_hi:[1,0]
	v_pk_mul_f32 v[34:35], v[34:35], v[10:11] op_sel_hi:[1,0]
	v_pk_mul_f32 v[32:33], v[32:33], v[10:11] op_sel_hi:[1,0]
.LB_rescA1:
	ds_read_b128 v[10:13], v0 offset:64
	ds_read_b128 v[180:183], v0 offset:96
	ds_read_b128 v[96:99], v0 offset:4672
	ds_read_b128 v[184:187], v0 offset:4704
	s_setprio 1
	s_waitcnt lgkmcnt(3)
	v_mfma_f32_32x32x16_bf16 v[80:95], v[10:13], v[164:167], 0
	s_waitcnt lgkmcnt(1)
	v_mfma_f32_32x32x16_bf16 v[96:111], v[96:99], v[164:167], 0
	v_mfma_f32_32x32x16_bf16 v[80:95], v[180:183], v[168:171], v[80:95]
	s_waitcnt lgkmcnt(0)
	v_mfma_f32_32x32x16_bf16 v[96:111], v[184:187], v[168:171], v[96:111]
	s_setprio 0
	v_add_u32_e32 v0, v238, v237
	ds_read_b64_tr_b16 v[190:191], v0 offset:28800
	ds_read_b64_tr_b16 v[180:181], v0 offset:29952
	ds_read_b64_tr_b16 v[182:183], v0 offset:31104
	ds_read_b64_tr_b16 v[10:11], v0 offset:32256
	ds_read_b64_tr_b16 v[188:189], v0 offset:27648
	ds_read_b64_tr_b16 v[12:13], v0 offset:33408
	ds_read_b64_tr_b16 v[184:185], v0 offset:34560
	ds_read_b64_tr_b16 v[186:187], v0 offset:35712
	s_nop 1
	v_max_f32_e32 v15, v97, v97
	v_max_f32_e32 v230, v96, v96
	v_max_f32_e32 v15, v230, v15
	v_max3_f32 v14, v80, v81, v82
	v_max3_f32 v15, v15, v98, v99
	v_max3_f32 v14, v14, v83, v84
	v_max3_f32 v15, v15, v100, v101
	v_max3_f32 v14, v14, v85, v86
	v_max3_f32 v15, v15, v102, v103
	v_max3_f32 v14, v14, v87, v88
	v_max3_f32 v15, v15, v104, v105
	v_max3_f32 v14, v14, v89, v90
	v_max3_f32 v15, v15, v106, v107
	v_max3_f32 v14, v14, v91, v92
	v_max3_f32 v15, v15, v108, v109
	v_max3_f32 v14, v14, v93, v94
	v_max3_f32 v15, v15, v110, v111
	v_max3_f32 v14, v14, v95, v15
	v_mov_b32_e32 v15, v14
	s_nop 1
	v_permlane32_swap_b32_e32 v14, v15
	v_max_f32_e32 v15, v15, v15
	v_max_f32_e32 v14, v14, v14
	v_max_f32_e32 v14, v14, v15
	v_cvt_pk_bf16_f32 v14, v14, v14
	v_lshlrev_b32_e32 v14, 16, v14
	v_sub_f32_e32 v15, v14, v210
	v_cmp_gt_f32_e64 s[4:5], s22, v210
	v_cmp_lt_f32_e32 vcc, s23, v15
	s_or_b64 vcc, s[4:5], vcc
	s_cbranch_vccz .LB_rescB1
	v_cndmask_b32_e32 v15, v210, v14, vcc
	v_sub_f32_e32 v14, v210, v15
	v_exp_f32_e32 v14, v14
	v_mov_b32_e32 v210, v15
	v_cndmask_b32_e64 v14, v14, 1.0, s[4:5]
	v_mul_f32_e32 v236, v236, v14
	v_pk_mul_f32 v[62:63], v[62:63], v[14:15] op_sel_hi:[1,0]
	v_pk_mul_f32 v[60:61], v[60:61], v[14:15] op_sel_hi:[1,0]
	v_pk_mul_f32 v[58:59], v[58:59], v[14:15] op_sel_hi:[1,0]
	v_pk_mul_f32 v[56:57], v[56:57], v[14:15] op_sel_hi:[1,0]
	v_pk_mul_f32 v[54:55], v[54:55], v[14:15] op_sel_hi:[1,0]
	v_pk_mul_f32 v[52:53], v[52:53], v[14:15] op_sel_hi:[1,0]
	v_pk_mul_f32 v[50:51], v[50:51], v[14:15] op_sel_hi:[1,0]
	v_pk_mul_f32 v[48:49], v[48:49], v[14:15] op_sel_hi:[1,0]
	v_pk_mul_f32 v[30:31], v[30:31], v[14:15] op_sel_hi:[1,0]
	v_pk_mul_f32 v[28:29], v[28:29], v[14:15] op_sel_hi:[1,0]
	v_pk_mul_f32 v[26:27], v[26:27], v[14:15] op_sel_hi:[1,0]
	v_pk_mul_f32 v[24:25], v[24:25], v[14:15] op_sel_hi:[1,0]
	v_pk_mul_f32 v[22:23], v[22:23], v[14:15] op_sel_hi:[1,0]
	v_pk_mul_f32 v[20:21], v[20:21], v[14:15] op_sel_hi:[1,0]
	v_pk_mul_f32 v[18:19], v[18:19], v[14:15] op_sel_hi:[1,0]
	v_pk_mul_f32 v[16:17], v[16:17], v[14:15] op_sel_hi:[1,0]

; #define LAS __attribute__((address_space(3)))
; DI float fast_exp2(float x) { return __builtin_amdgcn_exp2f(x); }
; template <int DQK, int NMAP>
; DI void att_qk(const LAS unsigned char* Kb, int r, int h, const bf16x8 (&qfm)[DQK / NMAP / 16], int mp, f32x16 (&S)[2]) {
;     ...
;         bf16x8 kf[2 * CH];
; #pragma unroll
;         for (int s = 0; s < CH; ++s) { kf[2 * s] = *(const LAS bf16x8*)(kp + 32 * (c * CH + s)); kf[2 * s + 1] = *(const LAS bf16x8*)(kp + 32 * KP + 32 * (c * CH + s)); }
;         __builtin_amdgcn_sched_barrier(0);
;         __builtin_amdgcn_s_setprio(1);
; #pragma unroll
;         for (int s = 0; s < CH; ++s) {
;             if (c == 0 && s == 0) { S[0] = __builtin_amdgcn_mfma_f32_32x32x16_bf16(kf[0], qfm[0], z, 0, 0, 0); S[1] = __builtin_amdgcn_mfma_f32_32x32x16_bf16(kf[1], qfm[0], z, 0, 0, 0); }
;             else { S[0] = __builtin_amdgcn_mfma_f32_32x32x16_bf16(kf[2 * s], qfm[c * CH + s], S[0], 0, 0, 0); S[1] = __builtin_amdgcn_mfma_f32_32x32x16_bf16(kf[2 * s + 1], qfm[c * CH + s], S[1], 0, 0, 0); }
;         }
;         __builtin_amdgcn_s_setprio(0);
;         __builtin_amdgcn_sched_barrier(0);
; template <int MODE>
; DI void att_sm_head(f32x16 (&S)[2], float& mrefm, float& lrunm, f32x16 (&om)[2], bool latent, const MaskP& mk, int h) {
;     ...
;         float ma = fmaxf(fmaxf(s0[0], s0[1]), s0[2]), mb = fmaxf(fmaxf(s1[0], s1[1]), s1[2]);
; #pragma unroll
;         for (int i = 3; i < 15; i += 2) { ma = fmaxf(fmaxf(ma, s0[i]), s0[i + 1]); mb = fmaxf(fmaxf(mb, s1[i]), s1[i + 1]); }
;         ma = fmaxf(fmaxf(ma, s0[15]), fmaxf(mb, s1[15]));
;         { auto rr = __builtin_amdgcn_permlane32_swap(__float_as_uint(ma), __float_as_uint(ma), false, false); ma = fmaxf(__uint_as_float(rr[0]), __uint_as_float(rr[1])); }
;         const bool uninit = mrefm < -1e29f;
;         const bool need = uninit || (ma - mrefm > 8.0f);
;         if (__any(need)) {
;             const float mnew = need ? ma : mrefm;
;             const float f = uninit ? 1.0f : fast_exp2(mrefm - mnew);
;             mrefm = mnew; lrunm *= f;
; #pragma unroll
;             for (int e = 0; e < 2; ++e)
; #pragma unroll
;                 for (int i = 0; i < 16; ++i) om[e][i] *= f;
;         }
.LB_rescA2:
	ds_read_b128 v[10:13], v0 offset:64
	ds_read_b128 v[180:183], v0 offset:96
	ds_read_b128 v[96:99], v0 offset:4672
	ds_read_b128 v[184:187], v0 offset:4704
	s_setprio 1
	s_waitcnt lgkmcnt(3)
	v_mfma_f32_32x32x16_bf16 v[80:95], v[10:13], v[164:167], 0
	s_waitcnt lgkmcnt(1)
	v_mfma_f32_32x32x16_bf16 v[96:111], v[96:99], v[164:167], 0
	v_mfma_f32_32x32x16_bf16 v[80:95], v[180:183], v[168:171], v[80:95]
	s_waitcnt lgkmcnt(0)
	v_mfma_f32_32x32x16_bf16 v[96:111], v[184:187], v[168:171], v[96:111]
	s_setprio 0
	v_add_u32_e32 v0, v238, v237
	ds_read_b64_tr_b16 v[188:189], v0 offset:36864
	ds_read_b64_tr_b16 v[190:191], v0 offset:38016
	ds_read_b64_tr_b16 v[184:185], v0 offset:39168
	ds_read_b64_tr_b16 v[186:187], v0 offset:40320
	ds_read_b64_tr_b16 v[180:181], v0 offset:41472
	ds_read_b64_tr_b16 v[182:183], v0 offset:42624
	ds_read_b64_tr_b16 v[10:11], v0 offset:43776
	ds_read_b64_tr_b16 v[12:13], v0 offset:44928
	s_nop 1
	v_max_f32_e32 v15, v97, v97
	v_max_f32_e32 v230, v96, v96
	v_max_f32_e32 v15, v230, v15
	v_max3_f32 v14, v80, v81, v82
	v_max3_f32 v15, v15, v98, v99
	v_max3_f32 v14, v14, v83, v84
	v_max3_f32 v15, v15, v100, v101
	v_max3_f32 v14, v14, v85, v86
	v_max3_f32 v15, v15, v102, v103
	v_max3_f32 v14, v14, v87, v88
	v_max3_f32 v15, v15, v104, v105
	v_max3_f32 v14, v14, v89, v90
	v_max3_f32 v15, v15, v106, v107
	v_max3_f32 v14, v14, v91, v92
	v_max3_f32 v15, v15, v108, v109
	v_max3_f32 v14, v14, v93, v94
	v_max3_f32 v15, v15, v110, v111
	v_max3_f32 v14, v14, v95, v15
	v_mov_b32_e32 v15, v14
	s_nop 1
	v_permlane32_swap_b32_e32 v14, v15
	v_max_f32_e32 v15, v15, v15
	v_max_f32_e32 v14, v14, v14
	v_max_f32_e32 v14, v14, v15
	v_cvt_pk_bf16_f32 v14, v14, v14
	v_lshlrev_b32_e32 v14, 16, v14
	v_sub_f32_e32 v15, v14, v210
	v_cmp_gt_f32_e64 s[4:5], s22, v210
	v_cmp_lt_f32_e32 vcc, s23, v15
	s_or_b64 vcc, s[4:5], vcc
	s_cbranch_vccz .LB_rescB2
	v_cndmask_b32_e32 v15, v210, v14, vcc
	v_sub_f32_e32 v14, v210, v15
	v_exp_f32_e32 v14, v14
	v_mov_b32_e32 v210, v15
	v_cndmask_b32_e64 v14, v14, 1.0, s[4:5]
	v_mul_f32_e32 v236, v236, v14
	v_pk_mul_f32 v[62:63], v[62:63], v[14:15] op_sel_hi:[1,0]
	v_pk_mul_f32 v[60:61], v[60:61], v[14:15] op_sel_hi:[1,0]
	v_pk_mul_f32 v[58:59], v[58:59], v[14:15] op_sel_hi:[1,0]
	v_pk_mul_f32 v[56:57], v[56:57], v[14:15] op_sel_hi:[1,0]
	v_pk_mul_f32 v[54:55], v[54:55], v[14:15] op_sel_hi:[1,0]
	v_pk_mul_f32 v[52:53], v[52:53], v[14:15] op_sel_hi:[1,0]
	v_pk_mul_f32 v[50:51], v[50:51], v[14:15] op_sel_hi:[1,0]
	v_pk_mul_f32 v[48:49], v[48:49], v[14:15] op_sel_hi:[1,0]
	v_pk_mul_f32 v[30:31], v[30:31], v[14:15] op_sel_hi:[1,0]
	v_pk_mul_f32 v[28:29], v[28:29], v[14:15] op_sel_hi:[1,0]
	v_pk_mul_f32 v[26:27], v[26:27], v[14:15] op_sel_hi:[1,0]
	v_pk_mul_f32 v[24:25], v[24:25], v[14:15] op_sel_hi:[1,0]
	v_pk_mul_f32 v[22:23], v[22:23], v[14:15] op_sel_hi:[1,0]
	v_pk_mul_f32 v[20:21], v[20:21], v[14:15] op_sel_hi:[1,0]
	v_pk_mul_f32 v[18:19], v[18:19], v[14:15] op_sel_hi:[1,0]
	v_pk_mul_f32 v[16:17], v[16:17], v[14:15] op_sel_hi:[1,0]
